# Up0/Up1 GEMM: first two vmcnt waits of each tile's first K-iteration relaxed from 8 to 24 (only loads older than the 16 epilogue stores must retire) so stores drain in background
# baseline (speedup 1.0000x reference)
; #define PH(k) if (p.ph_lo <= (k) && (k) < p.ph_hi)
; #define GEMM(EPI, e, A_, W_, N_, K_) { pg8::Gemm g{A_, W_, T_TOK, N_, K_}; pg8::StaticOrder S; S.init(T_TOK, N_, (int)gridDim.x, (int)blockIdx.x); \
;         pg8::gemm_phase<EPI, pg8::StaticOrder, true, true>(l3, g, S, e); }
;     __host__ __device__ bool next(int i, Unit& u) const {
;         const long L = (long)i * G + c; if (L >= nwg) return false;
;         int wgid = (int)L; { const int q = nwg / NXCD, r = nwg % NXCD, xcd = wgid % NXCD, off = wgid / NXCD; wgid = (xcd < r ? xcd * (q + 1) : r * (q + 1) + (xcd - r) * q) + off; }
;         const int nig = WGM * nN, gid = wgid / nig, fm = gid * WGM, gsz = (nM - fm) < WGM ? (nM - fm) : WGM;
;         u.pm = fm + ((wgid % nig) % gsz); u.pn = (wgid % nig) / gsz; return true;
; template <class Epi, class Sched, bool ALIGN_EPI = false, bool SP2 = false>
; __device__ __forceinline__ void gemm_phase(PG8_LAS unsigned char* lds, const Gemm g, const Sched& S, const Epi& E) {
;     ...
;     Unit cur, nxt; int ui = 0;
;     if (!S.next(0, cur)) return;
; __global__ void __launch_bounds__(NTHREADS) fwd_megakernel(Params p) {
;     ...
;     PH(5) { EpiUp2 e{sumsq + T_TOK, U}; GEMM(EpiUp2, e, hb, (const bf16_t*)(ws + WS_WT_UP0), 4096, 1024) }
.LBB0_1454:
	s_or_b64 exec, exec, s[2:3]
	s_mov_b32 s92, 0
	v_cmp_gt_i32_e32 vcc, 6, v1
	v_cmp_lt_i32_e64 s[2:3], 5, v5
	s_and_b64 s[0:1], vcc, s[2:3]
	s_and_saveexec_b64 s[4:5], s[0:1]
	s_cbranch_execz .LBB0_1479
	v_and_b32_e32 v10, 0x3ff, v0
	s_cmpk_gt_i32 s33, 0x7ff
	v_readfirstlane_b32 s0, v10
	s_cbranch_scc1 .LBB0_1479
	s_ashr_i32 s38, s33, 31
	s_lshr_b32 s1, s38, 29
	s_add_i32 s1, s33, s1
	s_and_b32 s2, s1, -8
	s_sub_i32 s7, s33, s2
	s_cmp_gt_i32 s7, -1
	s_cbranch_scc0 .LBB0_1458
	s_lshl_b32 s6, s7, 8
	s_cbranch_execz .LBB0_1459
	s_branch .LBB0_1460

; #define PG8_STAGE(bufoff, gbase, voff) do { _Pragma("unroll") for (int _i = 0; _i < 2; ++_i) \
;         __builtin_amdgcn_global_load_lds((const unsigned*)((const char*)(gbase) + (voff)[_i]), (PG8_LAS unsigned*)(lds + (bufoff) + ldsw + _i * 8192), 16, 0, 0); } while (0)
; #define PG8_LDA(dst, b, h) do { _Pragma("unroll") for (int m = 0; m < 4; ++m) _Pragma("unroll") for (int k = 0; k < 2; ++k) dst[m][k] = *(const PG8_LAS bf16x8*)(lds + PG8_SA(b, h) + aoff + m * 2048 + k * 1024); } while (0)
; #define PG8_LDB(dst, b, h) do { _Pragma("unroll") for (int n = 0; n < 2; ++n) _Pragma("unroll") for (int k = 0; k < 2; ++k) dst[n][k] = *(const PG8_LAS bf16x8*)(lds + PG8_SB(b, h) + boff + n * 2048 + k * 1024); } while (0)
; #define PG8_MMA(ai, bj, At, Bt) do { __builtin_amdgcn_s_setprio(1); _Pragma("unroll") for (int m = 0; m < 4; ++m) _Pragma("unroll") for (int n = 0; n < 2; ++n) _Pragma("unroll") for (int k = 0; k < 2; ++k) \
;         acc[ai][bj][m][n] = __builtin_amdgcn_mfma_f32_16x16x32_bf16(Bt[n][k], At[m][k], acc[ai][bj][m][n], 0, 0, 0); __builtin_amdgcn_s_setprio(0); } while (0)
; #define PG8_WAIT_V(n) asm volatile("s_waitcnt vmcnt(" #n ")" ::: "memory")
; #define PG8_WAIT_L(n) asm volatile("s_waitcnt lgkmcnt(" #n ")" ::: "memory")
; #define PG8_BAR __builtin_amdgcn_s_barrier()
; #define PG8_SCHED __builtin_amdgcn_sched_barrier(0)
; template <class Epi, class Sched, bool ALIGN_EPI = false, bool SP2 = false>
; __device__ __forceinline__ void gemm_phase(PG8_LAS unsigned char* lds, const Gemm g, const Sched& S, const Epi& E) {
;     ...
;             PG8_LDB(B0, 0, 0); PG8_LDB(B1, 0, 1); PG8_SCHED; PG8_LDA(At, 0, 0); PG8_STAGE(PG8_SA(1, 1), a1 + hstep, voffA);
;             PG8_WAIT_V(8); PG8_WAIT_L(0); PG8_BAR; PG8_MMA(0, 0, At, B0); PG8_MMA(0, 1, At, B1); PG8_BAR; PG8_SCHED;
;             PG8_LDA(At, 0, 1); PG8_STAGE(PG8_SB(0, 0), b2, voffB); PG8_STAGE(PG8_SB(0, 1), b2 + hstep, voffB); PG8_STAGE(PG8_SA(0, 0), a2, voffA);
;             PG8_WAIT_V(8); PG8_WAIT_L(0); PG8_BAR; PG8_MMA(1, 0, At, B0); PG8_MMA(1, 1, At, B1); PG8_BAR; PG8_SCHED;
.LBB0_1472:
	ds_read_b128 v[154:157], v150
	ds_read_b128 v[158:161], v150 offset:1024
	ds_read_b128 v[162:165], v150 offset:2048
	ds_read_b128 v[166:169], v150 offset:3072
	ds_read_b128 v[170:173], v151
	ds_read_b128 v[174:177], v151 offset:1024
	ds_read_b128 v[178:181], v151 offset:2048
	ds_read_b128 v[182:185], v151 offset:3072
	s_add_u32 s0, s30, 0xfffc0080
	s_addc_u32 s1, s31, -1
	s_cmp_eq_u32 s72, 12
	s_cselect_b32 s37, s23, s1
	s_cselect_b32 s36, s58, s0
	s_cselect_b32 s35, s21, s61
	s_cselect_b32 s34, s59, s60
	v_lshl_add_u64 v[146:147], s[30:31], 0, v[138:139]
	s_add_i32 m0, s29, 0xc000
	ds_read_b128 v[186:189], v152
	ds_read_b128 v[190:193], v152 offset:1024
	ds_read_b128 v[194:197], v152 offset:2048
	ds_read_b128 v[198:201], v152 offset:3072
	ds_read_b128 v[202:205], v152 offset:4096
	ds_read_b128 v[206:209], v152 offset:5120
	ds_read_b128 v[212:215], v152 offset:6144
	ds_read_b128 v[216:219], v152 offset:7168
	global_load_lds_dwordx4 v[146:147], off
	v_lshl_add_u64 v[146:147], s[30:31], 0, v[140:141]
	s_add_i32 m0, s29, 0xe000
	s_nop 0
	global_load_lds_dwordx4 v[146:147], off
	s_cmp_lg_u32 s92, 0
	s_cbranch_scc1 .Lrlx_u0_0
	s_waitcnt vmcnt(8)
.Lrlx_u0_0:
	s_waitcnt vmcnt(24)
	s_waitcnt lgkmcnt(0)
	s_barrier
	s_setprio 1
	s_waitcnt lgkmcnt(0)
	v_mfma_f32_16x16x32_bf16 v[126:129], v[154:157], v[186:189], v[126:129]
	v_mfma_f32_16x16x32_bf16 v[122:125], v[162:165], v[186:189], v[122:125]
	v_mfma_f32_16x16x32_bf16 v[110:113], v[154:157], v[194:197], v[110:113]
	v_mfma_f32_16x16x32_bf16 v[106:109], v[162:165], v[194:197], v[106:109]
	v_mfma_f32_16x16x32_bf16 v[94:97], v[154:157], v[202:205], v[94:97]
	v_mfma_f32_16x16x32_bf16 v[90:93], v[162:165], v[202:205], v[90:93]
	v_mfma_f32_16x16x32_bf16 v[78:81], v[154:157], v[212:215], v[78:81]
	v_mfma_f32_16x16x32_bf16 v[74:77], v[162:165], v[212:215], v[74:77]
	v_mfma_f32_16x16x32_bf16 v[126:129], v[158:161], v[190:193], v[126:129]
	v_mfma_f32_16x16x32_bf16 v[122:125], v[166:169], v[190:193], v[122:125]
	v_mfma_f32_16x16x32_bf16 v[110:113], v[158:161], v[198:201], v[110:113]
	v_mfma_f32_16x16x32_bf16 v[106:109], v[166:169], v[198:201], v[106:109]
	v_mfma_f32_16x16x32_bf16 v[94:97], v[158:161], v[206:209], v[94:97]
	v_mfma_f32_16x16x32_bf16 v[90:93], v[166:169], v[206:209], v[90:93]
	v_mfma_f32_16x16x32_bf16 v[78:81], v[158:161], v[216:219], v[78:81]
	v_mfma_f32_16x16x32_bf16 v[74:77], v[166:169], v[216:219], v[74:77]
	s_setprio 0
	s_setprio 1
	v_mfma_f32_16x16x32_bf16 v[118:121], v[170:173], v[186:189], v[118:121]
	v_mfma_f32_16x16x32_bf16 v[114:117], v[178:181], v[186:189], v[114:117]
	v_mfma_f32_16x16x32_bf16 v[102:105], v[170:173], v[194:197], v[102:105]
	v_mfma_f32_16x16x32_bf16 v[98:101], v[178:181], v[194:197], v[98:101]
	v_mfma_f32_16x16x32_bf16 v[86:89], v[170:173], v[202:205], v[86:89]
	v_mfma_f32_16x16x32_bf16 v[82:85], v[178:181], v[202:205], v[82:85]
	v_mfma_f32_16x16x32_bf16 v[70:73], v[170:173], v[212:215], v[70:73]
	v_mfma_f32_16x16x32_bf16 v[66:69], v[178:181], v[212:215], v[66:69]
	v_mfma_f32_16x16x32_bf16 v[118:121], v[174:177], v[190:193], v[118:121]
	v_mfma_f32_16x16x32_bf16 v[114:117], v[182:185], v[190:193], v[114:117]
	v_mfma_f32_16x16x32_bf16 v[102:105], v[174:177], v[198:201], v[102:105]
	v_mfma_f32_16x16x32_bf16 v[98:101], v[182:185], v[198:201], v[98:101]
	v_mfma_f32_16x16x32_bf16 v[86:89], v[174:177], v[206:209], v[86:89]
	v_mfma_f32_16x16x32_bf16 v[82:85], v[182:185], v[206:209], v[82:85]
	v_mfma_f32_16x16x32_bf16 v[70:73], v[174:177], v[216:219], v[70:73]
	v_mfma_f32_16x16x32_bf16 v[66:69], v[182:185], v[216:219], v[66:69]
	s_setprio 0
	s_barrier
	s_add_i32 s0, s51, s41
	v_lshl_add_u64 v[146:147], s[34:35], 0, v[132:133]
	s_mov_b32 m0, s0
	ds_read_b128 v[186:189], v152 offset:16384
	ds_read_b128 v[190:193], v152 offset:17408
	ds_read_b128 v[194:197], v152 offset:18432
	ds_read_b128 v[198:201], v152 offset:19456
	ds_read_b128 v[202:205], v152 offset:20480
	ds_read_b128 v[206:209], v152 offset:21504
	ds_read_b128 v[212:215], v152 offset:22528
	ds_read_b128 v[216:219], v152 offset:23552
	global_load_lds_dwordx4 v[146:147], off
	s_add_i32 m0, s0, 0x2000
	s_add_u32 s0, s34, 0x40000
	v_lshl_add_u64 v[220:221], s[34:35], 0, v[136:137]
	s_addc_u32 s1, s35, 0
	s_add_i32 s73, s52, s41
	global_load_lds_dwordx4 v[220:221], off
	v_lshl_add_u64 v[222:223], s[0:1], 0, v[132:133]
	s_mov_b32 m0, s73
	v_lshl_add_u64 v[224:225], s[36:37], 0, v[134:135]
	global_load_lds_dwordx4 v[222:223], off
	v_lshl_add_u64 v[222:223], s[0:1], 0, v[136:137]
	s_add_i32 m0, s73, 0x2000
	s_nop 0
	global_load_lds_dwordx4 v[222:223], off
	v_lshl_add_u64 v[222:223], s[36:37], 0, v[130:131]
	s_mov_b32 m0, s29
	s_nop 0
	global_load_lds_dwordx4 v[222:223], off
	s_mov_b32 m0, s44
	s_nop 0
	global_load_lds_dwordx4 v[224:225], off
	s_cmp_lg_u32 s92, 0
	s_cbranch_scc1 .Lrlx_u0_1
	s_waitcnt vmcnt(8)
; #define PG8_STAGE(bufoff, gbase, voff) do { _Pragma("unroll") for (int _i = 0; _i < 2; ++_i) \
;         __builtin_amdgcn_global_load_lds((const unsigned*)((const char*)(gbase) + (voff)[_i]), (PG8_LAS unsigned*)(lds + (bufoff) + ldsw + _i * 8192), 16, 0, 0); } while (0)
; #define PG8_LDA(dst, b, h) do { _Pragma("unroll") for (int m = 0; m < 4; ++m) _Pragma("unroll") for (int k = 0; k < 2; ++k) dst[m][k] = *(const PG8_LAS bf16x8*)(lds + PG8_SA(b, h) + aoff + m * 2048 + k * 1024); } while (0)
; #define PG8_LDB(dst, b, h) do { _Pragma("unroll") for (int n = 0; n < 2; ++n) _Pragma("unroll") for (int k = 0; k < 2; ++k) dst[n][k] = *(const PG8_LAS bf16x8*)(lds + PG8_SB(b, h) + boff + n * 2048 + k * 1024); } while (0)
; #define PG8_MMA(ai, bj, At, Bt) do { __builtin_amdgcn_s_setprio(1); _Pragma("unroll") for (int m = 0; m < 4; ++m) _Pragma("unroll") for (int n = 0; n < 2; ++n) _Pragma("unroll") for (int k = 0; k < 2; ++k) \
;         acc[ai][bj][m][n] = __builtin_amdgcn_mfma_f32_16x16x32_bf16(Bt[n][k], At[m][k], acc[ai][bj][m][n], 0, 0, 0); __builtin_amdgcn_s_setprio(0); } while (0)
; #define PG8_WAIT_V(n) asm volatile("s_waitcnt vmcnt(" #n ")" ::: "memory")
; #define PG8_WAIT_L(n) asm volatile("s_waitcnt lgkmcnt(" #n ")" ::: "memory")
; #define PG8_BAR __builtin_amdgcn_s_barrier()
; #define PG8_SCHED __builtin_amdgcn_sched_barrier(0)
; template <class Epi, class Sched, bool ALIGN_EPI = false, bool SP2 = false>
; __device__ __forceinline__ void gemm_phase(PG8_LAS unsigned char* lds, const Gemm g, const Sched& S, const Epi& E) {
;     ...
;             PG8_WAIT_V(8); PG8_WAIT_L(0); PG8_BAR; PG8_MMA(1, 0, At, B0); PG8_MMA(1, 1, At, B1); PG8_BAR; PG8_SCHED;
;             PG8_LDB(B0, 1, 0); PG8_LDB(B1, 1, 1); PG8_SCHED; PG8_LDA(At, 1, 0); PG8_STAGE(PG8_SA(0, 1), a2 + hstep, voffA);
;             PG8_WAIT_V(8); PG8_WAIT_L(0); PG8_BAR; PG8_MMA(0, 0, At, B0); PG8_MMA(0, 1, At, B1); PG8_BAR; PG8_SCHED;
.Lrlx_u0_1:
	s_waitcnt vmcnt(24)
	s_mov_b32 s92, 0
	s_waitcnt lgkmcnt(0)
	s_barrier
	s_setprio 1
	s_waitcnt lgkmcnt(0)
	v_mfma_f32_16x16x32_bf16 v[62:65], v[154:157], v[186:189], v[62:65]
	v_mfma_f32_16x16x32_bf16 v[58:61], v[162:165], v[186:189], v[58:61]
	v_mfma_f32_16x16x32_bf16 v[50:53], v[154:157], v[194:197], v[50:53]
	v_mfma_f32_16x16x32_bf16 v[42:45], v[162:165], v[194:197], v[42:45]
	v_mfma_f32_16x16x32_bf16 v[34:37], v[154:157], v[202:205], v[34:37]
	v_mfma_f32_16x16x32_bf16 v[26:29], v[162:165], v[202:205], v[26:29]
	v_mfma_f32_16x16x32_bf16 v[18:21], v[154:157], v[212:215], v[18:21]
	v_mfma_f32_16x16x32_bf16 v[10:13], v[162:165], v[212:215], v[10:13]
	v_mfma_f32_16x16x32_bf16 v[62:65], v[158:161], v[190:193], v[62:65]
	v_mfma_f32_16x16x32_bf16 v[58:61], v[166:169], v[190:193], v[58:61]
	v_mfma_f32_16x16x32_bf16 v[50:53], v[158:161], v[198:201], v[50:53]
	v_mfma_f32_16x16x32_bf16 v[42:45], v[166:169], v[198:201], v[42:45]
	v_mfma_f32_16x16x32_bf16 v[34:37], v[158:161], v[206:209], v[34:37]
	v_mfma_f32_16x16x32_bf16 v[26:29], v[166:169], v[206:209], v[26:29]
	v_mfma_f32_16x16x32_bf16 v[18:21], v[158:161], v[216:219], v[18:21]
	v_mfma_f32_16x16x32_bf16 v[10:13], v[166:169], v[216:219], v[10:13]
	s_setprio 0
	s_setprio 1
	v_mfma_f32_16x16x32_bf16 v[54:57], v[170:173], v[186:189], v[54:57]
	v_mfma_f32_16x16x32_bf16 v[46:49], v[178:181], v[186:189], v[46:49]
	v_mfma_f32_16x16x32_bf16 v[38:41], v[170:173], v[194:197], v[38:41]
	v_mfma_f32_16x16x32_bf16 v[30:33], v[178:181], v[194:197], v[30:33]
	v_mfma_f32_16x16x32_bf16 v[22:25], v[170:173], v[202:205], v[22:25]
	v_mfma_f32_16x16x32_bf16 v[14:17], v[178:181], v[202:205], v[14:17]
	v_mfma_f32_16x16x32_bf16 v[6:9], v[170:173], v[212:215], v[6:9]
	v_mfma_f32_16x16x32_bf16 v[2:5], v[178:181], v[212:215], v[2:5]
	v_mfma_f32_16x16x32_bf16 v[54:57], v[174:177], v[190:193], v[54:57]
	v_mfma_f32_16x16x32_bf16 v[46:49], v[182:185], v[190:193], v[46:49]
	v_mfma_f32_16x16x32_bf16 v[38:41], v[174:177], v[198:201], v[38:41]
	v_mfma_f32_16x16x32_bf16 v[30:33], v[182:185], v[198:201], v[30:33]
	v_mfma_f32_16x16x32_bf16 v[22:25], v[174:177], v[206:209], v[22:25]
	v_mfma_f32_16x16x32_bf16 v[14:17], v[182:185], v[206:209], v[14:17]
	v_mfma_f32_16x16x32_bf16 v[6:9], v[174:177], v[216:219], v[6:9]
	v_mfma_f32_16x16x32_bf16 v[2:5], v[182:185], v[216:219], v[2:5]
	s_setprio 0
	s_barrier
	s_add_i32 s73, 0, 0x18000
	v_add_u32_e32 v153, s73, v148
	s_add_i32 s74, 0, 0x1c000
	ds_read_b128 v[154:157], v153
	ds_read_b128 v[158:161], v153 offset:1024
	ds_read_b128 v[162:165], v153 offset:2048
	ds_read_b128 v[166:169], v153 offset:3072
	v_add_u32_e32 v153, s74, v148
	ds_read_b128 v[170:173], v153
	ds_read_b128 v[174:177], v153 offset:1024
	ds_read_b128 v[178:181], v153 offset:2048
	ds_read_b128 v[182:185], v153 offset:3072
	s_add_u32 s0, s36, 0x40000
	s_addc_u32 s1, s37, 0
	s_mov_b32 m0, s45
	v_lshl_add_u64 v[226:227], s[0:1], 0, v[130:131]
	ds_read_b128 v[186:189], v152 offset:32768
	ds_read_b128 v[190:193], v152 offset:33792
	ds_read_b128 v[194:197], v152 offset:34816
	ds_read_b128 v[198:201], v152 offset:35840
	ds_read_b128 v[202:205], v152 offset:36864
	ds_read_b128 v[206:209], v152 offset:37888
	ds_read_b128 v[212:215], v152 offset:38912
	ds_read_b128 v[216:219], v152 offset:39936
	global_load_lds_dwordx4 v[226:227], off
	v_lshl_add_u64 v[226:227], s[0:1], 0, v[134:135]
	s_mov_b32 m0, s46
	s_nop 0
	global_load_lds_dwordx4 v[226:227], off
	s_waitcnt vmcnt(8)
	s_waitcnt lgkmcnt(0)
	s_barrier
	s_setprio 1
	s_waitcnt lgkmcnt(0)
	v_mfma_f32_16x16x32_bf16 v[126:129], v[154:157], v[186:189], v[126:129]
	v_mfma_f32_16x16x32_bf16 v[122:125], v[162:165], v[186:189], v[122:125]
	v_mfma_f32_16x16x32_bf16 v[110:113], v[154:157], v[194:197], v[110:113]
	v_mfma_f32_16x16x32_bf16 v[106:109], v[162:165], v[194:197], v[106:109]
	v_mfma_f32_16x16x32_bf16 v[94:97], v[154:157], v[202:205], v[94:97]
	v_mfma_f32_16x16x32_bf16 v[90:93], v[162:165], v[202:205], v[90:93]
	v_mfma_f32_16x16x32_bf16 v[78:81], v[154:157], v[212:215], v[78:81]
	v_mfma_f32_16x16x32_bf16 v[74:77], v[162:165], v[212:215], v[74:77]
	v_mfma_f32_16x16x32_bf16 v[126:129], v[158:161], v[190:193], v[126:129]
	v_mfma_f32_16x16x32_bf16 v[122:125], v[166:169], v[190:193], v[122:125]
	v_mfma_f32_16x16x32_bf16 v[110:113], v[158:161], v[198:201], v[110:113]
	v_mfma_f32_16x16x32_bf16 v[106:109], v[166:169], v[198:201], v[106:109]
	v_mfma_f32_16x16x32_bf16 v[94:97], v[158:161], v[206:209], v[94:97]
	v_mfma_f32_16x16x32_bf16 v[90:93], v[166:169], v[206:209], v[90:93]
	v_mfma_f32_16x16x32_bf16 v[78:81], v[158:161], v[216:219], v[78:81]
	v_mfma_f32_16x16x32_bf16 v[74:77], v[166:169], v[216:219], v[74:77]
	s_setprio 0
	s_setprio 1
	v_mfma_f32_16x16x32_bf16 v[118:121], v[170:173], v[186:189], v[118:121]
	v_mfma_f32_16x16x32_bf16 v[114:117], v[178:181], v[186:189], v[114:117]
	v_mfma_f32_16x16x32_bf16 v[102:105], v[170:173], v[194:197], v[102:105]
	v_mfma_f32_16x16x32_bf16 v[98:101], v[178:181], v[194:197], v[98:101]
	v_mfma_f32_16x16x32_bf16 v[86:89], v[170:173], v[202:205], v[86:89]
	v_mfma_f32_16x16x32_bf16 v[82:85], v[178:181], v[202:205], v[82:85]
	v_mfma_f32_16x16x32_bf16 v[70:73], v[170:173], v[212:215], v[70:73]
	v_mfma_f32_16x16x32_bf16 v[66:69], v[178:181], v[212:215], v[66:69]
	v_mfma_f32_16x16x32_bf16 v[118:121], v[174:177], v[190:193], v[118:121]
	v_mfma_f32_16x16x32_bf16 v[114:117], v[182:185], v[190:193], v[114:117]
	v_mfma_f32_16x16x32_bf16 v[102:105], v[174:177], v[198:201], v[102:105]
	v_mfma_f32_16x16x32_bf16 v[98:101], v[182:185], v[198:201], v[98:101]
	v_mfma_f32_16x16x32_bf16 v[86:89], v[174:177], v[206:209], v[86:89]
	v_mfma_f32_16x16x32_bf16 v[82:85], v[182:185], v[206:209], v[82:85]
	v_mfma_f32_16x16x32_bf16 v[70:73], v[174:177], v[216:219], v[70:73]
	v_mfma_f32_16x16x32_bf16 v[66:69], v[182:185], v[216:219], v[66:69]
	s_setprio 0
	s_barrier
; DI unsigned pk_bf16(float a, float b) { f32x2 v = {a, b}; bf2_t r = __builtin_convertvector(v, bf2_t); return __builtin_bit_cast(unsigned, r); }
; #define PG8_STAGE(bufoff, gbase, voff) do { _Pragma("unroll") for (int _i = 0; _i < 2; ++_i) \
;         __builtin_amdgcn_global_load_lds((const unsigned*)((const char*)(gbase) + (voff)[_i]), (PG8_LAS unsigned*)(lds + (bufoff) + ldsw + _i * 8192), 16, 0, 0); } while (0)
; #define PG8_LDA(dst, b, h) do { _Pragma("unroll") for (int m = 0; m < 4; ++m) _Pragma("unroll") for (int k = 0; k < 2; ++k) dst[m][k] = *(const PG8_LAS bf16x8*)(lds + PG8_SA(b, h) + aoff + m * 2048 + k * 1024); } while (0)
; #define PG8_WAIT_V(n) asm volatile("s_waitcnt vmcnt(" #n ")" ::: "memory")
; template <class Epi, class Sched, bool ALIGN_EPI = false, bool SP2 = false>
; __device__ __forceinline__ void gemm_phase(PG8_LAS unsigned char* lds, const Gemm g, const Sched& S, const Epi& E) {
;     ...
;             PG8_LDB(B0, 1, 0); PG8_LDB(B1, 1, 1); PG8_SCHED; PG8_LDA(At, 1, 0); PG8_STAGE(PG8_SA(0, 1), a2 + hstep, voffA);
;             PG8_WAIT_V(8); PG8_WAIT_L(0); PG8_BAR; PG8_MMA(0, 0, At, B0); PG8_MMA(0, 1, At, B1); PG8_BAR; PG8_SCHED;
;             PG8_LDA(At, 1, 1); PG8_STAGE(PG8_SB(1, 0), b3, voffB); PG8_STAGE(PG8_SB(1, 1), b3 + hstep, voffB); PG8_STAGE(PG8_SA(1, 0), a3, voffA);
;             PG8_WAIT_V(8); PG8_WAIT_L(0); PG8_BAR; PG8_MMA(1, 0, At, B0); PG8_MMA(1, 1, At, B1); PG8_BAR; PG8_SCHED;
;     DI void operator()(const pg8::f32x4 (&acc)[2][2][4][2], const pg8::Unit& u, int wr, int wc, int fr, int fq) const {
;         const int row0 = u.pm * 256 + wr * 64 + fr, col0 = u.pn * 256 + wc * 32 + 8 * fq;
; #pragma unroll
;         for (int ai = 0; ai < 2; ++ai)
; #pragma unroll
;             for (int m = 0; m < 4; ++m) {
;                 const int row = row0 + ai * 128 + m * 16;
;                 bf16_t* rp = U + (size_t)row * 4096 + col0;
; #pragma unroll
;                 for (int bj = 0; bj < 2; ++bj) {
;                     float v[8];
; #pragma unroll
;                     for (int n = 0; n < 2; ++n)
; #pragma unroll
;                         for (int e = 0; e < 4; ++e) { const float t = fmaxf(acc[ai][bj][m][n][e], 0.f); v[4 * n + e] = t * t; }
;                     u32x4 w; w.x = pk_bf16(v[0], v[1]); w.y = pk_bf16(v[2], v[3]); w.z = pk_bf16(v[4], v[5]); w.w = pk_bf16(v[6], v[7]);
;                     *(u32x4*)(rp + bj * 128) = w;
	s_add_i32 s0, s73, s41
	v_lshl_add_u64 v[146:147], v[146:147], 0, s[8:9]
	s_mov_b32 m0, s0
	ds_read_b128 v[186:189], v152 offset:49152
	ds_read_b128 v[190:193], v152 offset:50176
	ds_read_b128 v[194:197], v152 offset:51200
	ds_read_b128 v[198:201], v152 offset:52224
	ds_read_b128 v[202:205], v152 offset:53248
	ds_read_b128 v[206:209], v152 offset:54272
	ds_read_b128 v[212:215], v152 offset:55296
	ds_read_b128 v[216:219], v152 offset:56320
	global_load_lds_dwordx4 v[146:147], off
	s_add_i32 m0, s0, 0x2000
	s_add_u32 s0, s34, 0x40080
	v_lshl_add_u64 v[146:147], v[220:221], 0, s[8:9]
	s_addc_u32 s1, s35, 0
	s_add_i32 s34, s74, s41
	global_load_lds_dwordx4 v[146:147], off
	v_lshl_add_u64 v[146:147], s[0:1], 0, v[132:133]
	s_mov_b32 m0, s34
	s_nop 0
	global_load_lds_dwordx4 v[146:147], off
	v_lshl_add_u64 v[146:147], s[0:1], 0, v[136:137]
	s_add_i32 m0, s34, 0x2000
	s_nop 0
	global_load_lds_dwordx4 v[146:147], off
	v_lshl_add_u64 v[146:147], v[222:223], 0, s[8:9]
	s_mov_b32 m0, s48
	s_nop 0
	global_load_lds_dwordx4 v[146:147], off
	v_lshl_add_u64 v[146:147], v[224:225], 0, s[8:9]
	s_mov_b32 m0, s49
	s_nop 0
	global_load_lds_dwordx4 v[146:147], off
	s_waitcnt vmcnt(8)
	s_waitcnt lgkmcnt(0)
	s_barrier
	s_setprio 1
	s_waitcnt lgkmcnt(0)
	v_mfma_f32_16x16x32_bf16 v[62:65], v[154:157], v[186:189], v[62:65]
	v_mfma_f32_16x16x32_bf16 v[58:61], v[162:165], v[186:189], v[58:61]
	v_mfma_f32_16x16x32_bf16 v[50:53], v[154:157], v[194:197], v[50:53]
	v_mfma_f32_16x16x32_bf16 v[42:45], v[162:165], v[194:197], v[42:45]
	v_mfma_f32_16x16x32_bf16 v[34:37], v[154:157], v[202:205], v[34:37]
	v_mfma_f32_16x16x32_bf16 v[26:29], v[162:165], v[202:205], v[26:29]
	v_mfma_f32_16x16x32_bf16 v[18:21], v[154:157], v[212:215], v[18:21]
	v_mfma_f32_16x16x32_bf16 v[10:13], v[162:165], v[212:215], v[10:13]
	v_mfma_f32_16x16x32_bf16 v[62:65], v[158:161], v[190:193], v[62:65]
	v_mfma_f32_16x16x32_bf16 v[58:61], v[166:169], v[190:193], v[58:61]
	v_mfma_f32_16x16x32_bf16 v[50:53], v[158:161], v[198:201], v[50:53]
	v_mfma_f32_16x16x32_bf16 v[42:45], v[166:169], v[198:201], v[42:45]
	v_mfma_f32_16x16x32_bf16 v[34:37], v[158:161], v[206:209], v[34:37]
	v_mfma_f32_16x16x32_bf16 v[26:29], v[166:169], v[206:209], v[26:29]
	v_mfma_f32_16x16x32_bf16 v[18:21], v[158:161], v[216:219], v[18:21]
	v_mfma_f32_16x16x32_bf16 v[10:13], v[166:169], v[216:219], v[10:13]
	s_setprio 0
	s_setprio 1
	v_mfma_f32_16x16x32_bf16 v[54:57], v[170:173], v[186:189], v[54:57]
	v_mfma_f32_16x16x32_bf16 v[46:49], v[178:181], v[186:189], v[46:49]
	v_mfma_f32_16x16x32_bf16 v[38:41], v[170:173], v[194:197], v[38:41]
	v_mfma_f32_16x16x32_bf16 v[30:33], v[178:181], v[194:197], v[30:33]
	v_mfma_f32_16x16x32_bf16 v[22:25], v[170:173], v[202:205], v[22:25]
	v_mfma_f32_16x16x32_bf16 v[14:17], v[178:181], v[202:205], v[14:17]
	v_mfma_f32_16x16x32_bf16 v[6:9], v[170:173], v[212:215], v[6:9]
	v_mfma_f32_16x16x32_bf16 v[2:5], v[178:181], v[212:215], v[2:5]
	v_mfma_f32_16x16x32_bf16 v[54:57], v[174:177], v[190:193], v[54:57]
	v_mfma_f32_16x16x32_bf16 v[46:49], v[182:185], v[190:193], v[46:49]
	v_mfma_f32_16x16x32_bf16 v[38:41], v[174:177], v[198:201], v[38:41]
	v_mfma_f32_16x16x32_bf16 v[30:33], v[182:185], v[198:201], v[30:33]
	v_mfma_f32_16x16x32_bf16 v[22:25], v[174:177], v[206:209], v[22:25]
	v_mfma_f32_16x16x32_bf16 v[14:17], v[182:185], v[206:209], v[14:17]
	v_mfma_f32_16x16x32_bf16 v[6:9], v[174:177], v[216:219], v[6:9]
	v_mfma_f32_16x16x32_bf16 v[2:5], v[182:185], v[216:219], v[2:5]
	s_setprio 0
	s_barrier
	s_add_i32 s72, s72, 2
	s_add_u32 s30, s30, 0x100
	s_addc_u32 s31, s31, 0
	s_add_u32 s60, s60, 0x100
	s_addc_u32 s61, s61, 0
	s_cmp_gt_u32 s72, 13
	s_cbranch_scc0 .LBB0_1472
	s_and_b64 vcc, exec, s[10:11]
	s_cbranch_vccz .LBB0_1475
	s_barrier
.LBB0_1475:
	s_mov_b32 s92, 1
	v_lshl_add_u32 v154, s28, 8, v1
	v_lshl_or_b32 v146, s57, 8, v149
	v_ashrrev_i32_e32 v155, 31, v154
	v_ashrrev_i32_e32 v147, 31, v146
	v_lshlrev_b64 v[156:157], 13, v[154:155]
	v_lshl_add_u64 v[156:157], s[66:67], 0, v[156:157]
	v_lshlrev_b64 v[158:159], 1, v[146:147]
	v_max_f32_e32 v122, 0, v122
	v_max_f32_e32 v123, 0, v123
	v_lshl_add_u64 v[146:147], v[156:157], 0, v[158:159]
	v_pk_mul_f32 v[156:157], v[122:123], v[122:123]
	v_max_f32_e32 v126, 0, v126
	v_max_f32_e32 v127, 0, v127
	v_max_f32_e32 v128, 0, v128
	v_max_f32_e32 v129, 0, v129
	v_max_f32_e32 v122, 0, v124
	v_max_f32_e32 v123, 0, v125
	v_pk_mul_f32 v[126:127], v[126:127], v[126:127]
	v_pk_mul_f32 v[128:129], v[128:129], v[128:129]
	v_pk_mul_f32 v[160:161], v[122:123], v[122:123]
	v_cvt_pk_bf16_f32 v122, v126, v127
	v_cvt_pk_bf16_f32 v123, v128, v129
	v_cvt_pk_bf16_f32 v124, v156, v157
	v_cvt_pk_bf16_f32 v125, v160, v161
	v_max_f32_e32 v114, 0, v114
	v_max_f32_e32 v115, 0, v115
	global_store_dwordx4 v[146:147], v[122:125], off
	s_nop 1
	v_pk_mul_f32 v[122:123], v[114:115], v[114:115]
	v_max_f32_e32 v118, 0, v118
	v_max_f32_e32 v119, 0, v119
	v_max_f32_e32 v120, 0, v120
	v_max_f32_e32 v121, 0, v121
	v_max_f32_e32 v114, 0, v116
	v_max_f32_e32 v115, 0, v117
	v_pk_mul_f32 v[118:119], v[118:119], v[118:119]
	v_pk_mul_f32 v[120:121], v[120:121], v[120:121]
	v_pk_mul_f32 v[124:125], v[114:115], v[114:115]
	v_cvt_pk_bf16_f32 v114, v118, v119
	v_cvt_pk_bf16_f32 v115, v120, v121
	v_cvt_pk_bf16_f32 v116, v122, v123
	v_cvt_pk_bf16_f32 v117, v124, v125
	global_store_dwordx4 v[146:147], v[114:117], off offset:256
	v_max_f32_e32 v106, 0, v106
	v_max_f32_e32 v107, 0, v107
	v_or_b32_e32 v114, 16, v154
	v_ashrrev_i32_e32 v115, 31, v114
	v_pk_mul_f32 v[116:117], v[106:107], v[106:107]
	v_lshlrev_b64 v[114:115], 13, v[114:115]
	v_max_f32_e32 v110, 0, v110
	v_max_f32_e32 v111, 0, v111
	v_max_f32_e32 v112, 0, v112
; DI unsigned pk_bf16(float a, float b) { f32x2 v = {a, b}; bf2_t r = __builtin_convertvector(v, bf2_t); return __builtin_bit_cast(unsigned, r); }
;     DI void operator()(const pg8::f32x4 (&acc)[2][2][4][2], const pg8::Unit& u, int wr, int wc, int fr, int fq) const {
;     ...
;             for (int m = 0; m < 4; ++m) {
;                 const int row = row0 + ai * 128 + m * 16;
;                 bf16_t* rp = U + (size_t)row * 4096 + col0;
; #pragma unroll
;                 for (int bj = 0; bj < 2; ++bj) {
;                     float v[8];
; #pragma unroll
;                     for (int n = 0; n < 2; ++n)
; #pragma unroll
;                         for (int e = 0; e < 4; ++e) { const float t = fmaxf(acc[ai][bj][m][n][e], 0.f); v[4 * n + e] = t * t; }
;                     u32x4 w; w.x = pk_bf16(v[0], v[1]); w.y = pk_bf16(v[2], v[3]); w.z = pk_bf16(v[4], v[5]); w.w = pk_bf16(v[6], v[7]);
;                     *(u32x4*)(rp + bj * 128) = w;
	v_max_f32_e32 v113, 0, v113
	v_max_f32_e32 v106, 0, v108
	v_max_f32_e32 v107, 0, v109
	v_lshl_add_u64 v[114:115], s[66:67], 0, v[114:115]
	v_pk_mul_f32 v[110:111], v[110:111], v[110:111]
	v_pk_mul_f32 v[112:113], v[112:113], v[112:113]
	v_pk_mul_f32 v[118:119], v[106:107], v[106:107]
	v_lshl_add_u64 v[114:115], v[114:115], 0, v[158:159]
	v_cvt_pk_bf16_f32 v106, v110, v111
	v_cvt_pk_bf16_f32 v107, v112, v113
	v_cvt_pk_bf16_f32 v108, v116, v117
	v_cvt_pk_bf16_f32 v109, v118, v119
	v_max_f32_e32 v98, 0, v98
	v_max_f32_e32 v99, 0, v99
	global_store_dwordx4 v[114:115], v[106:109], off
	s_nop 1
	v_pk_mul_f32 v[106:107], v[98:99], v[98:99]
	v_max_f32_e32 v102, 0, v102
	v_max_f32_e32 v103, 0, v103
	v_max_f32_e32 v104, 0, v104
	v_max_f32_e32 v105, 0, v105
	v_max_f32_e32 v98, 0, v100
	v_max_f32_e32 v99, 0, v101
	v_pk_mul_f32 v[102:103], v[102:103], v[102:103]
	v_pk_mul_f32 v[104:105], v[104:105], v[104:105]
	v_pk_mul_f32 v[108:109], v[98:99], v[98:99]
	v_cvt_pk_bf16_f32 v98, v102, v103
	v_cvt_pk_bf16_f32 v99, v104, v105
	v_cvt_pk_bf16_f32 v100, v106, v107
	v_cvt_pk_bf16_f32 v101, v108, v109
	global_store_dwordx4 v[114:115], v[98:101], off offset:256
	v_max_f32_e32 v90, 0, v90
	v_max_f32_e32 v91, 0, v91
	v_or_b32_e32 v98, 32, v154
	v_ashrrev_i32_e32 v99, 31, v98
	v_pk_mul_f32 v[100:101], v[90:91], v[90:91]
	v_lshlrev_b64 v[98:99], 13, v[98:99]
	v_max_f32_e32 v94, 0, v94
	v_max_f32_e32 v95, 0, v95
	v_max_f32_e32 v96, 0, v96
	v_max_f32_e32 v97, 0, v97
	v_max_f32_e32 v90, 0, v92
	v_max_f32_e32 v91, 0, v93
	v_lshl_add_u64 v[98:99], s[66:67], 0, v[98:99]
	v_pk_mul_f32 v[94:95], v[94:95], v[94:95]
	v_pk_mul_f32 v[96:97], v[96:97], v[96:97]
	v_pk_mul_f32 v[102:103], v[90:91], v[90:91]
	v_lshl_add_u64 v[98:99], v[98:99], 0, v[158:159]
	v_cvt_pk_bf16_f32 v90, v94, v95
	v_cvt_pk_bf16_f32 v91, v96, v97
	v_cvt_pk_bf16_f32 v92, v100, v101
	v_cvt_pk_bf16_f32 v93, v102, v103
	v_max_f32_e32 v82, 0, v82
	v_max_f32_e32 v83, 0, v83
	global_store_dwordx4 v[98:99], v[90:93], off
	s_nop 1
	v_pk_mul_f32 v[90:91], v[82:83], v[82:83]
	v_max_f32_e32 v86, 0, v86
	v_max_f32_e32 v87, 0, v87
	v_max_f32_e32 v88, 0, v88
	v_max_f32_e32 v89, 0, v89
	v_max_f32_e32 v82, 0, v84
	v_max_f32_e32 v83, 0, v85
	v_pk_mul_f32 v[86:87], v[86:87], v[86:87]
	v_pk_mul_f32 v[88:89], v[88:89], v[88:89]
	v_pk_mul_f32 v[92:93], v[82:83], v[82:83]
	v_cvt_pk_bf16_f32 v82, v86, v87
	v_cvt_pk_bf16_f32 v83, v88, v89
	v_cvt_pk_bf16_f32 v84, v90, v91
	v_cvt_pk_bf16_f32 v85, v92, v93
	global_store_dwordx4 v[98:99], v[82:85], off offset:256
	v_max_f32_e32 v74, 0, v74
	v_max_f32_e32 v75, 0, v75
	v_or_b32_e32 v82, 48, v154
	v_ashrrev_i32_e32 v83, 31, v82
	v_pk_mul_f32 v[84:85], v[74:75], v[74:75]
	v_lshlrev_b64 v[82:83], 13, v[82:83]
	v_max_f32_e32 v78, 0, v78
	v_max_f32_e32 v79, 0, v79
	v_max_f32_e32 v80, 0, v80
	v_max_f32_e32 v81, 0, v81
	v_max_f32_e32 v74, 0, v76
	v_max_f32_e32 v75, 0, v77
	v_lshl_add_u64 v[82:83], s[66:67], 0, v[82:83]
	v_pk_mul_f32 v[78:79], v[78:79], v[78:79]
	v_pk_mul_f32 v[80:81], v[80:81], v[80:81]
	v_pk_mul_f32 v[86:87], v[74:75], v[74:75]
	v_lshl_add_u64 v[82:83], v[82:83], 0, v[158:159]
	v_cvt_pk_bf16_f32 v74, v78, v79
	v_cvt_pk_bf16_f32 v75, v80, v81
	v_cvt_pk_bf16_f32 v76, v84, v85
	v_cvt_pk_bf16_f32 v77, v86, v87
	v_max_f32_e32 v66, 0, v66
	v_max_f32_e32 v67, 0, v67
	global_store_dwordx4 v[82:83], v[74:77], off
	s_nop 1
	v_pk_mul_f32 v[74:75], v[66:67], v[66:67]
	v_max_f32_e32 v70, 0, v70
	v_max_f32_e32 v71, 0, v71
	v_max_f32_e32 v72, 0, v72
	v_max_f32_e32 v73, 0, v73
	v_max_f32_e32 v66, 0, v68
	v_max_f32_e32 v67, 0, v69
	v_pk_mul_f32 v[70:71], v[70:71], v[70:71]
	v_pk_mul_f32 v[72:73], v[72:73], v[72:73]
	v_pk_mul_f32 v[76:77], v[66:67], v[66:67]
	v_cvt_pk_bf16_f32 v66, v70, v71
	v_cvt_pk_bf16_f32 v67, v72, v73
	v_cvt_pk_bf16_f32 v68, v74, v75
	v_cvt_pk_bf16_f32 v69, v76, v77
	v_max_f32_e32 v58, 0, v58
	v_max_f32_e32 v59, 0, v59
	global_store_dwordx4 v[82:83], v[66:69], off offset:256
	v_max_f32_e32 v62, 0, v62
	v_max_f32_e32 v63, 0, v63
	v_pk_mul_f32 v[68:69], v[58:59], v[58:59]
	v_pk_mul_f32 v[62:63], v[62:63], v[62:63]
	v_max_f32_e32 v64, 0, v64
	v_max_f32_e32 v65, 0, v65
	v_max_f32_e32 v58, 0, v60
	v_max_f32_e32 v59, 0, v61
	v_pk_mul_f32 v[64:65], v[64:65], v[64:65]
	v_pk_mul_f32 v[70:71], v[58:59], v[58:59]
	v_cvt_pk_bf16_f32 v58, v62, v63
	v_add_co_u32_e32 v62, vcc, s53, v146
	v_cvt_pk_bf16_f32 v59, v64, v65
	v_cvt_pk_bf16_f32 v60, v68, v69
	v_cvt_pk_bf16_f32 v61, v70, v71
	v_addc_co_u32_e32 v63, vcc, 0, v147, vcc
	v_max_f32_e32 v46, 0, v46
	v_max_f32_e32 v47, 0, v47
	global_store_dwordx4 v[62:63], v[58:61], off
	s_nop 1
	v_pk_mul_f32 v[58:59], v[46:47], v[46:47]
	v_max_f32_e32 v54, 0, v54
; DI unsigned pk_bf16(float a, float b) { f32x2 v = {a, b}; bf2_t r = __builtin_convertvector(v, bf2_t); return __builtin_bit_cast(unsigned, r); }
;     DI void operator()(const pg8::f32x4 (&acc)[2][2][4][2], const pg8::Unit& u, int wr, int wc, int fr, int fq) const {
;     ...
;             for (int m = 0; m < 4; ++m) {
;                 const int row = row0 + ai * 128 + m * 16;
;                 bf16_t* rp = U + (size_t)row * 4096 + col0;
; #pragma unroll
;                 for (int bj = 0; bj < 2; ++bj) {
;                     float v[8];
; #pragma unroll
;                     for (int n = 0; n < 2; ++n)
; #pragma unroll
;                         for (int e = 0; e < 4; ++e) { const float t = fmaxf(acc[ai][bj][m][n][e], 0.f); v[4 * n + e] = t * t; }
;                     u32x4 w; w.x = pk_bf16(v[0], v[1]); w.y = pk_bf16(v[2], v[3]); w.z = pk_bf16(v[4], v[5]); w.w = pk_bf16(v[6], v[7]);
;                     *(u32x4*)(rp + bj * 128) = w;
	v_max_f32_e32 v55, 0, v55
	v_max_f32_e32 v56, 0, v56
	v_max_f32_e32 v57, 0, v57
	v_max_f32_e32 v46, 0, v48
	v_max_f32_e32 v47, 0, v49
	v_pk_mul_f32 v[54:55], v[54:55], v[54:55]
	v_pk_mul_f32 v[56:57], v[56:57], v[56:57]
	v_pk_mul_f32 v[60:61], v[46:47], v[46:47]
	v_lshl_add_u64 v[66:67], v[146:147], 0, s[12:13]
	v_cvt_pk_bf16_f32 v46, v54, v55
	v_cvt_pk_bf16_f32 v47, v56, v57
	v_cvt_pk_bf16_f32 v48, v58, v59
	v_cvt_pk_bf16_f32 v49, v60, v61
	global_store_dwordx4 v[66:67], v[46:49], off offset:256
	v_max_f32_e32 v42, 0, v42
	v_max_f32_e32 v43, 0, v43
	v_max_f32_e32 v48, 0, v50
	v_max_f32_e32 v49, 0, v51
	v_max_f32_e32 v50, v52, v52
	v_max_f32_e32 v51, v53, v53
	v_pk_mul_f32 v[52:53], v[42:43], v[42:43]
	v_pk_mul_f32 v[48:49], v[48:49], v[48:49]
	v_max_f32_e32 v50, 0, v50
	v_max_f32_e32 v51, 0, v51
	v_max_f32_e32 v42, 0, v44
	v_max_f32_e32 v43, 0, v45
	v_pk_mul_f32 v[50:51], v[50:51], v[50:51]
	v_pk_mul_f32 v[54:55], v[42:43], v[42:43]
	v_cvt_pk_bf16_f32 v42, v48, v49
	v_add_co_u32_e32 v48, vcc, s54, v146
	v_cvt_pk_bf16_f32 v43, v50, v51
	v_cvt_pk_bf16_f32 v44, v52, v53
	v_cvt_pk_bf16_f32 v45, v54, v55
	v_addc_co_u32_e32 v49, vcc, 0, v147, vcc
	v_max_f32_e32 v30, 0, v30
	v_max_f32_e32 v31, 0, v31
	global_store_dwordx4 v[48:49], v[42:45], off
	s_nop 1
	v_pk_mul_f32 v[42:43], v[30:31], v[30:31]
	v_max_f32_e32 v38, 0, v38
	v_max_f32_e32 v39, 0, v39
	v_max_f32_e32 v40, 0, v40
	v_max_f32_e32 v41, 0, v41
	v_max_f32_e32 v30, 0, v32
	v_max_f32_e32 v31, 0, v33
	v_pk_mul_f32 v[38:39], v[38:39], v[38:39]
	v_pk_mul_f32 v[40:41], v[40:41], v[40:41]
	v_pk_mul_f32 v[44:45], v[30:31], v[30:31]
	v_lshl_add_u64 v[46:47], v[146:147], 0, s[14:15]
	v_cvt_pk_bf16_f32 v30, v38, v39
	v_cvt_pk_bf16_f32 v31, v40, v41
	v_cvt_pk_bf16_f32 v32, v42, v43
	v_cvt_pk_bf16_f32 v33, v44, v45
	global_store_dwordx4 v[46:47], v[30:33], off offset:256
	v_max_f32_e32 v26, 0, v26
	v_max_f32_e32 v27, 0, v27
	v_max_f32_e32 v32, 0, v34
	v_max_f32_e32 v33, 0, v35
	v_max_f32_e32 v34, v36, v36
	v_max_f32_e32 v35, v37, v37
	v_pk_mul_f32 v[36:37], v[26:27], v[26:27]
	v_pk_mul_f32 v[32:33], v[32:33], v[32:33]
	v_max_f32_e32 v34, 0, v34
	v_max_f32_e32 v35, 0, v35
	v_max_f32_e32 v26, 0, v28
	v_max_f32_e32 v27, 0, v29
	v_pk_mul_f32 v[34:35], v[34:35], v[34:35]
	v_pk_mul_f32 v[38:39], v[26:27], v[26:27]
	v_cvt_pk_bf16_f32 v26, v32, v33
	v_add_co_u32_e32 v32, vcc, s55, v146
	v_cvt_pk_bf16_f32 v27, v34, v35
	v_cvt_pk_bf16_f32 v28, v36, v37
	v_cvt_pk_bf16_f32 v29, v38, v39
	v_addc_co_u32_e32 v33, vcc, 0, v147, vcc
	v_max_f32_e32 v14, 0, v14
	v_max_f32_e32 v15, 0, v15
	global_store_dwordx4 v[32:33], v[26:29], off
	s_nop 1
	v_pk_mul_f32 v[26:27], v[14:15], v[14:15]
	v_max_f32_e32 v22, 0, v22
	v_max_f32_e32 v23, 0, v23
	v_max_f32_e32 v24, 0, v24
	v_max_f32_e32 v25, 0, v25
	v_max_f32_e32 v14, 0, v16
	v_max_f32_e32 v15, 0, v17
	v_pk_mul_f32 v[22:23], v[22:23], v[22:23]
	v_pk_mul_f32 v[24:25], v[24:25], v[24:25]
	v_pk_mul_f32 v[28:29], v[14:15], v[14:15]
	v_lshl_add_u64 v[30:31], v[146:147], 0, s[16:17]
	v_cvt_pk_bf16_f32 v14, v22, v23
	v_cvt_pk_bf16_f32 v15, v24, v25
	v_cvt_pk_bf16_f32 v16, v26, v27
	v_cvt_pk_bf16_f32 v17, v28, v29
	global_store_dwordx4 v[30:31], v[14:17], off offset:256
	v_max_f32_e32 v10, 0, v10
	v_max_f32_e32 v11, 0, v11
	v_max_f32_e32 v16, 0, v18
	v_max_f32_e32 v17, 0, v19
	v_max_f32_e32 v18, v20, v20
	v_max_f32_e32 v19, v21, v21
	v_pk_mul_f32 v[20:21], v[10:11], v[10:11]
	v_pk_mul_f32 v[16:17], v[16:17], v[16:17]
	v_max_f32_e32 v18, 0, v18
	v_max_f32_e32 v19, 0, v19
	v_max_f32_e32 v10, 0, v12
	v_max_f32_e32 v11, 0, v13
	v_pk_mul_f32 v[18:19], v[18:19], v[18:19]
	v_pk_mul_f32 v[22:23], v[10:11], v[10:11]
	v_cvt_pk_bf16_f32 v10, v16, v17
	v_add_co_u32_e32 v16, vcc, s56, v146
	v_cvt_pk_bf16_f32 v11, v18, v19
	v_cvt_pk_bf16_f32 v12, v20, v21
	v_cvt_pk_bf16_f32 v13, v22, v23
	v_addc_co_u32_e32 v17, vcc, 0, v147, vcc
	v_max_f32_e32 v2, 0, v2
	v_max_f32_e32 v3, 0, v3
	global_store_dwordx4 v[16:17], v[10:13], off
	s_nop 1
	v_pk_mul_f32 v[10:11], v[2:3], v[2:3]
	v_max_f32_e32 v6, 0, v6
	v_max_f32_e32 v7, 0, v7
	v_max_f32_e32 v8, 0, v8
	v_max_f32_e32 v9, 0, v9
	v_max_f32_e32 v2, 0, v4
	v_max_f32_e32 v3, 0, v5
	v_pk_mul_f32 v[6:7], v[6:7], v[6:7]
	v_pk_mul_f32 v[8:9], v[8:9], v[8:9]
	v_pk_mul_f32 v[12:13], v[2:3], v[2:3]
	v_lshl_add_u64 v[14:15], v[146:147], 0, s[18:19]
	v_cvt_pk_bf16_f32 v2, v6, v7
	v_cvt_pk_bf16_f32 v3, v8, v9
	v_cvt_pk_bf16_f32 v4, v10, v11
	v_cvt_pk_bf16_f32 v5, v12, v13
	s_andn2_b64 vcc, exec, s[2:3]
	s_mov_b64 s[2:3], -1
	global_store_dwordx4 v[14:15], v[2:5], off offset:256
	s_cbranch_vccnz .LBB0_1464
	s_andn2_b64 vcc, exec, s[6:7]
	s_cbranch_vccnz .LBB0_1463
	s_barrier
	s_branch .LBB0_1463

;     __host__ __device__ bool next(int i, Unit& u) const {
;         const long L = (long)i * G + c; if (L >= nwg) return false;
;         int wgid = (int)L; { const int q = nwg / NXCD, r = nwg % NXCD, xcd = wgid % NXCD, off = wgid / NXCD; wgid = (xcd < r ? xcd * (q + 1) : r * (q + 1) + (xcd - r) * q) + off; }
;         const int nig = WGM * nN, gid = wgid / nig, fm = gid * WGM, gsz = (nM - fm) < WGM ? (nM - fm) : WGM;
;         u.pm = fm + ((wgid % nig) % gsz); u.pn = (wgid % nig) / gsz; return true;
.LBB0_3705:
	s_or_b64 exec, exec, s[2:3]
	s_mov_b32 s92, 0
	v_cmp_gt_i32_e32 vcc, 13, v1
	v_cmp_lt_i32_e64 s[2:3], 12, v5
	s_and_b64 s[0:1], vcc, s[2:3]
	s_and_saveexec_b64 s[4:5], s[0:1]
	s_cbranch_execz .LBB0_3730
	v_and_b32_e32 v10, 0x3ff, v0
	s_cmpk_gt_i32 s33, 0x7ff
	v_readfirstlane_b32 s0, v10
	s_cbranch_scc1 .LBB0_3730
	s_ashr_i32 s38, s33, 31
	s_lshr_b32 s1, s38, 29
	s_add_i32 s1, s33, s1
	s_and_b32 s2, s1, -8
	s_sub_i32 s7, s33, s2
	s_cmp_gt_i32 s7, -1
	s_cbranch_scc0 .LBB0_3709
	s_lshl_b32 s6, s7, 8
	s_cbranch_execz .LBB0_3710
	s_branch .LBB0_3711

; #define PG8_STAGE(bufoff, gbase, voff) do { _Pragma("unroll") for (int _i = 0; _i < 2; ++_i) \
;         __builtin_amdgcn_global_load_lds((const unsigned*)((const char*)(gbase) + (voff)[_i]), (PG8_LAS unsigned*)(lds + (bufoff) + ldsw + _i * 8192), 16, 0, 0); } while (0)
; #define PG8_LDA(dst, b, h) do { _Pragma("unroll") for (int m = 0; m < 4; ++m) _Pragma("unroll") for (int k = 0; k < 2; ++k) dst[m][k] = *(const PG8_LAS bf16x8*)(lds + PG8_SA(b, h) + aoff + m * 2048 + k * 1024); } while (0)
; #define PG8_LDB(dst, b, h) do { _Pragma("unroll") for (int n = 0; n < 2; ++n) _Pragma("unroll") for (int k = 0; k < 2; ++k) dst[n][k] = *(const PG8_LAS bf16x8*)(lds + PG8_SB(b, h) + boff + n * 2048 + k * 1024); } while (0)
; #define PG8_MMA(ai, bj, At, Bt) do { __builtin_amdgcn_s_setprio(1); _Pragma("unroll") for (int m = 0; m < 4; ++m) _Pragma("unroll") for (int n = 0; n < 2; ++n) _Pragma("unroll") for (int k = 0; k < 2; ++k) \
;         acc[ai][bj][m][n] = __builtin_amdgcn_mfma_f32_16x16x32_bf16(Bt[n][k], At[m][k], acc[ai][bj][m][n], 0, 0, 0); __builtin_amdgcn_s_setprio(0); } while (0)
; #define PG8_WAIT_V(n) asm volatile("s_waitcnt vmcnt(" #n ")" ::: "memory")
; #define PG8_WAIT_L(n) asm volatile("s_waitcnt lgkmcnt(" #n ")" ::: "memory")
; #define PG8_BAR __builtin_amdgcn_s_barrier()
; #define PG8_SCHED __builtin_amdgcn_sched_barrier(0)
; template <class Epi, class Sched, bool ALIGN_EPI = false, bool SP2 = false>
; __device__ __forceinline__ void gemm_phase(PG8_LAS unsigned char* lds, const Gemm g, const Sched& S, const Epi& E) {
;     ...
;             const bool last = (t == nt - 2);
;             const char* a1 = cA + (size_t)(t + 1) * kstep;
;             const char* a2 = last ? nA : cA + (size_t)(t + 2) * kstep; const char* b2 = last ? nB : cB + (size_t)(t + 2) * kstep;
;             const char* a3 = a2 + kstep; const char* b3 = b2 + kstep;
;             if (last && has_next) S.a_ready(nxt);
;             if constexpr (SP2) {
;             PG8_LDB(B0, 0, 0); PG8_LDB(B1, 0, 1); PG8_SCHED; PG8_LDA(At, 0, 0); PG8_STAGE(PG8_SA(1, 1), a1 + hstep, voffA);
;             PG8_WAIT_V(8); PG8_WAIT_L(0); PG8_BAR; PG8_MMA(0, 0, At, B0); PG8_MMA(0, 1, At, B1); PG8_BAR; PG8_SCHED;
;             PG8_LDA(At, 0, 1); PG8_STAGE(PG8_SB(0, 0), b2, voffB); PG8_STAGE(PG8_SB(0, 1), b2 + hstep, voffB); PG8_STAGE(PG8_SA(0, 0), a2, voffA);
.LBB0_3723:
	ds_read_b128 v[154:157], v150
	ds_read_b128 v[158:161], v150 offset:1024
	ds_read_b128 v[162:165], v150 offset:2048
	ds_read_b128 v[166:169], v150 offset:3072
	ds_read_b128 v[170:173], v151
	ds_read_b128 v[174:177], v151 offset:1024
	ds_read_b128 v[178:181], v151 offset:2048
	ds_read_b128 v[182:185], v151 offset:3072
	s_add_u32 s0, s30, 0xfffc0080
	s_addc_u32 s1, s31, -1
	s_cmp_eq_u32 s68, 12
	s_cselect_b32 s37, s23, s1
	s_cselect_b32 s36, s58, s0
	s_cselect_b32 s35, s21, s61
	s_cselect_b32 s34, s59, s60
	v_lshl_add_u64 v[146:147], s[30:31], 0, v[138:139]
	s_add_i32 m0, s29, 0xc000
	ds_read_b128 v[186:189], v152
	ds_read_b128 v[190:193], v152 offset:1024
	ds_read_b128 v[194:197], v152 offset:2048
	ds_read_b128 v[198:201], v152 offset:3072
	ds_read_b128 v[202:205], v152 offset:4096
	ds_read_b128 v[206:209], v152 offset:5120
	ds_read_b128 v[212:215], v152 offset:6144
	ds_read_b128 v[216:219], v152 offset:7168
	global_load_lds_dwordx4 v[146:147], off
	v_lshl_add_u64 v[146:147], s[30:31], 0, v[140:141]
	s_add_i32 m0, s29, 0xe000
	s_nop 0
	global_load_lds_dwordx4 v[146:147], off
	s_cmp_lg_u32 s92, 0
	s_cbranch_scc1 .Lrlx_u1_0
	s_waitcnt vmcnt(8)
.Lrlx_u1_0:
	s_waitcnt vmcnt(24)
	s_waitcnt lgkmcnt(0)
	s_barrier
	s_setprio 1
	s_waitcnt lgkmcnt(0)
	v_mfma_f32_16x16x32_bf16 v[126:129], v[154:157], v[186:189], v[126:129]
	v_mfma_f32_16x16x32_bf16 v[122:125], v[162:165], v[186:189], v[122:125]
	v_mfma_f32_16x16x32_bf16 v[110:113], v[154:157], v[194:197], v[110:113]
	v_mfma_f32_16x16x32_bf16 v[106:109], v[162:165], v[194:197], v[106:109]
	v_mfma_f32_16x16x32_bf16 v[94:97], v[154:157], v[202:205], v[94:97]
	v_mfma_f32_16x16x32_bf16 v[90:93], v[162:165], v[202:205], v[90:93]
	v_mfma_f32_16x16x32_bf16 v[78:81], v[154:157], v[212:215], v[78:81]
	v_mfma_f32_16x16x32_bf16 v[74:77], v[162:165], v[212:215], v[74:77]
	v_mfma_f32_16x16x32_bf16 v[126:129], v[158:161], v[190:193], v[126:129]
	v_mfma_f32_16x16x32_bf16 v[122:125], v[166:169], v[190:193], v[122:125]
	v_mfma_f32_16x16x32_bf16 v[110:113], v[158:161], v[198:201], v[110:113]
	v_mfma_f32_16x16x32_bf16 v[106:109], v[166:169], v[198:201], v[106:109]
	v_mfma_f32_16x16x32_bf16 v[94:97], v[158:161], v[206:209], v[94:97]
	v_mfma_f32_16x16x32_bf16 v[90:93], v[166:169], v[206:209], v[90:93]
	v_mfma_f32_16x16x32_bf16 v[78:81], v[158:161], v[216:219], v[78:81]
	v_mfma_f32_16x16x32_bf16 v[74:77], v[166:169], v[216:219], v[74:77]
	s_setprio 0
	s_setprio 1
	v_mfma_f32_16x16x32_bf16 v[118:121], v[170:173], v[186:189], v[118:121]
	v_mfma_f32_16x16x32_bf16 v[114:117], v[178:181], v[186:189], v[114:117]
	v_mfma_f32_16x16x32_bf16 v[102:105], v[170:173], v[194:197], v[102:105]
	v_mfma_f32_16x16x32_bf16 v[98:101], v[178:181], v[194:197], v[98:101]
	v_mfma_f32_16x16x32_bf16 v[86:89], v[170:173], v[202:205], v[86:89]
	v_mfma_f32_16x16x32_bf16 v[82:85], v[178:181], v[202:205], v[82:85]
	v_mfma_f32_16x16x32_bf16 v[70:73], v[170:173], v[212:215], v[70:73]
	v_mfma_f32_16x16x32_bf16 v[66:69], v[178:181], v[212:215], v[66:69]
	v_mfma_f32_16x16x32_bf16 v[118:121], v[174:177], v[190:193], v[118:121]
	v_mfma_f32_16x16x32_bf16 v[114:117], v[182:185], v[190:193], v[114:117]
	v_mfma_f32_16x16x32_bf16 v[102:105], v[174:177], v[198:201], v[102:105]
	v_mfma_f32_16x16x32_bf16 v[98:101], v[182:185], v[198:201], v[98:101]
	v_mfma_f32_16x16x32_bf16 v[86:89], v[174:177], v[206:209], v[86:89]
	v_mfma_f32_16x16x32_bf16 v[82:85], v[182:185], v[206:209], v[82:85]
	v_mfma_f32_16x16x32_bf16 v[70:73], v[174:177], v[216:219], v[70:73]
	v_mfma_f32_16x16x32_bf16 v[66:69], v[182:185], v[216:219], v[66:69]
	s_setprio 0
	s_barrier
	s_add_i32 s0, s51, s41
	v_lshl_add_u64 v[146:147], s[34:35], 0, v[132:133]
	s_mov_b32 m0, s0
	ds_read_b128 v[186:189], v152 offset:16384
	ds_read_b128 v[190:193], v152 offset:17408
	ds_read_b128 v[194:197], v152 offset:18432
	ds_read_b128 v[198:201], v152 offset:19456
	ds_read_b128 v[202:205], v152 offset:20480
	ds_read_b128 v[206:209], v152 offset:21504
	ds_read_b128 v[212:215], v152 offset:22528
	ds_read_b128 v[216:219], v152 offset:23552
	global_load_lds_dwordx4 v[146:147], off
	s_add_i32 m0, s0, 0x2000
	s_add_u32 s0, s34, 0x40000
	v_lshl_add_u64 v[220:221], s[34:35], 0, v[136:137]
	s_addc_u32 s1, s35, 0
	s_add_i32 s69, s52, s41
	global_load_lds_dwordx4 v[220:221], off
	v_lshl_add_u64 v[222:223], s[0:1], 0, v[132:133]
	s_mov_b32 m0, s69
	v_lshl_add_u64 v[224:225], s[36:37], 0, v[134:135]
	global_load_lds_dwordx4 v[222:223], off
	v_lshl_add_u64 v[222:223], s[0:1], 0, v[136:137]
	s_add_i32 m0, s69, 0x2000
	s_nop 0
	global_load_lds_dwordx4 v[222:223], off
	v_lshl_add_u64 v[222:223], s[36:37], 0, v[130:131]
	s_mov_b32 m0, s29
	s_nop 0
	global_load_lds_dwordx4 v[222:223], off
	s_mov_b32 m0, s44
	s_nop 0
	global_load_lds_dwordx4 v[224:225], off
	s_cmp_lg_u32 s92, 0
	s_cbranch_scc1 .Lrlx_u1_1
	s_waitcnt vmcnt(8)
; #define PG8_STAGE(bufoff, gbase, voff) do { _Pragma("unroll") for (int _i = 0; _i < 2; ++_i) \
;         __builtin_amdgcn_global_load_lds((const unsigned*)((const char*)(gbase) + (voff)[_i]), (PG8_LAS unsigned*)(lds + (bufoff) + ldsw + _i * 8192), 16, 0, 0); } while (0)
; #define PG8_LDA(dst, b, h) do { _Pragma("unroll") for (int m = 0; m < 4; ++m) _Pragma("unroll") for (int k = 0; k < 2; ++k) dst[m][k] = *(const PG8_LAS bf16x8*)(lds + PG8_SA(b, h) + aoff + m * 2048 + k * 1024); } while (0)
; #define PG8_LDB(dst, b, h) do { _Pragma("unroll") for (int n = 0; n < 2; ++n) _Pragma("unroll") for (int k = 0; k < 2; ++k) dst[n][k] = *(const PG8_LAS bf16x8*)(lds + PG8_SB(b, h) + boff + n * 2048 + k * 1024); } while (0)
; #define PG8_MMA(ai, bj, At, Bt) do { __builtin_amdgcn_s_setprio(1); _Pragma("unroll") for (int m = 0; m < 4; ++m) _Pragma("unroll") for (int n = 0; n < 2; ++n) _Pragma("unroll") for (int k = 0; k < 2; ++k) \
;         acc[ai][bj][m][n] = __builtin_amdgcn_mfma_f32_16x16x32_bf16(Bt[n][k], At[m][k], acc[ai][bj][m][n], 0, 0, 0); __builtin_amdgcn_s_setprio(0); } while (0)
; #define PG8_WAIT_V(n) asm volatile("s_waitcnt vmcnt(" #n ")" ::: "memory")
; #define PG8_WAIT_L(n) asm volatile("s_waitcnt lgkmcnt(" #n ")" ::: "memory")
; #define PG8_BAR __builtin_amdgcn_s_barrier()
; #define PG8_SCHED __builtin_amdgcn_sched_barrier(0)
; template <class Epi, class Sched, bool ALIGN_EPI = false, bool SP2 = false>
; __device__ __forceinline__ void gemm_phase(PG8_LAS unsigned char* lds, const Gemm g, const Sched& S, const Epi& E) {
;     ...
;             PG8_WAIT_V(8); PG8_WAIT_L(0); PG8_BAR; PG8_MMA(1, 0, At, B0); PG8_MMA(1, 1, At, B1); PG8_BAR; PG8_SCHED;
;             PG8_LDB(B0, 1, 0); PG8_LDB(B1, 1, 1); PG8_SCHED; PG8_LDA(At, 1, 0); PG8_STAGE(PG8_SA(0, 1), a2 + hstep, voffA);
;             PG8_WAIT_V(8); PG8_WAIT_L(0); PG8_BAR; PG8_MMA(0, 0, At, B0); PG8_MMA(0, 1, At, B1); PG8_BAR; PG8_SCHED;
.Lrlx_u1_1:
	s_waitcnt vmcnt(24)
	s_mov_b32 s92, 0
	s_waitcnt lgkmcnt(0)
	s_barrier
	s_setprio 1
	s_waitcnt lgkmcnt(0)
	v_mfma_f32_16x16x32_bf16 v[62:65], v[154:157], v[186:189], v[62:65]
	v_mfma_f32_16x16x32_bf16 v[58:61], v[162:165], v[186:189], v[58:61]
	v_mfma_f32_16x16x32_bf16 v[50:53], v[154:157], v[194:197], v[50:53]
	v_mfma_f32_16x16x32_bf16 v[42:45], v[162:165], v[194:197], v[42:45]
	v_mfma_f32_16x16x32_bf16 v[34:37], v[154:157], v[202:205], v[34:37]
	v_mfma_f32_16x16x32_bf16 v[26:29], v[162:165], v[202:205], v[26:29]
	v_mfma_f32_16x16x32_bf16 v[18:21], v[154:157], v[212:215], v[18:21]
	v_mfma_f32_16x16x32_bf16 v[10:13], v[162:165], v[212:215], v[10:13]
	v_mfma_f32_16x16x32_bf16 v[62:65], v[158:161], v[190:193], v[62:65]
	v_mfma_f32_16x16x32_bf16 v[58:61], v[166:169], v[190:193], v[58:61]
	v_mfma_f32_16x16x32_bf16 v[50:53], v[158:161], v[198:201], v[50:53]
	v_mfma_f32_16x16x32_bf16 v[42:45], v[166:169], v[198:201], v[42:45]
	v_mfma_f32_16x16x32_bf16 v[34:37], v[158:161], v[206:209], v[34:37]
	v_mfma_f32_16x16x32_bf16 v[26:29], v[166:169], v[206:209], v[26:29]
	v_mfma_f32_16x16x32_bf16 v[18:21], v[158:161], v[216:219], v[18:21]
	v_mfma_f32_16x16x32_bf16 v[10:13], v[166:169], v[216:219], v[10:13]
	s_setprio 0
	s_setprio 1
	v_mfma_f32_16x16x32_bf16 v[54:57], v[170:173], v[186:189], v[54:57]
	v_mfma_f32_16x16x32_bf16 v[46:49], v[178:181], v[186:189], v[46:49]
	v_mfma_f32_16x16x32_bf16 v[38:41], v[170:173], v[194:197], v[38:41]
	v_mfma_f32_16x16x32_bf16 v[30:33], v[178:181], v[194:197], v[30:33]
	v_mfma_f32_16x16x32_bf16 v[22:25], v[170:173], v[202:205], v[22:25]
	v_mfma_f32_16x16x32_bf16 v[14:17], v[178:181], v[202:205], v[14:17]
	v_mfma_f32_16x16x32_bf16 v[6:9], v[170:173], v[212:215], v[6:9]
	v_mfma_f32_16x16x32_bf16 v[2:5], v[178:181], v[212:215], v[2:5]
	v_mfma_f32_16x16x32_bf16 v[54:57], v[174:177], v[190:193], v[54:57]
	v_mfma_f32_16x16x32_bf16 v[46:49], v[182:185], v[190:193], v[46:49]
	v_mfma_f32_16x16x32_bf16 v[38:41], v[174:177], v[198:201], v[38:41]
	v_mfma_f32_16x16x32_bf16 v[30:33], v[182:185], v[198:201], v[30:33]
	v_mfma_f32_16x16x32_bf16 v[22:25], v[174:177], v[206:209], v[22:25]
	v_mfma_f32_16x16x32_bf16 v[14:17], v[182:185], v[206:209], v[14:17]
	v_mfma_f32_16x16x32_bf16 v[6:9], v[174:177], v[216:219], v[6:9]
	v_mfma_f32_16x16x32_bf16 v[2:5], v[182:185], v[216:219], v[2:5]
	s_setprio 0
	s_barrier
	s_add_i32 s69, 0, 0x18000
	v_add_u32_e32 v153, s69, v148
	s_add_i32 s70, 0, 0x1c000
	ds_read_b128 v[154:157], v153
	ds_read_b128 v[158:161], v153 offset:1024
	ds_read_b128 v[162:165], v153 offset:2048
	ds_read_b128 v[166:169], v153 offset:3072
	v_add_u32_e32 v153, s70, v148
	ds_read_b128 v[170:173], v153
	ds_read_b128 v[174:177], v153 offset:1024
	ds_read_b128 v[178:181], v153 offset:2048
	ds_read_b128 v[182:185], v153 offset:3072
	s_add_u32 s0, s36, 0x40000
	s_addc_u32 s1, s37, 0
	s_mov_b32 m0, s45
	v_lshl_add_u64 v[226:227], s[0:1], 0, v[130:131]
	ds_read_b128 v[186:189], v152 offset:32768
	ds_read_b128 v[190:193], v152 offset:33792
	ds_read_b128 v[194:197], v152 offset:34816
	ds_read_b128 v[198:201], v152 offset:35840
	ds_read_b128 v[202:205], v152 offset:36864
	ds_read_b128 v[206:209], v152 offset:37888
	ds_read_b128 v[212:215], v152 offset:38912
	ds_read_b128 v[216:219], v152 offset:39936
	global_load_lds_dwordx4 v[226:227], off
	v_lshl_add_u64 v[226:227], s[0:1], 0, v[134:135]
	s_mov_b32 m0, s46
	s_nop 0
	global_load_lds_dwordx4 v[226:227], off
	s_waitcnt vmcnt(8)
	s_waitcnt lgkmcnt(0)
	s_barrier
	s_setprio 1
	s_waitcnt lgkmcnt(0)
	v_mfma_f32_16x16x32_bf16 v[126:129], v[154:157], v[186:189], v[126:129]
	v_mfma_f32_16x16x32_bf16 v[122:125], v[162:165], v[186:189], v[122:125]
	v_mfma_f32_16x16x32_bf16 v[110:113], v[154:157], v[194:197], v[110:113]
	v_mfma_f32_16x16x32_bf16 v[106:109], v[162:165], v[194:197], v[106:109]
	v_mfma_f32_16x16x32_bf16 v[94:97], v[154:157], v[202:205], v[94:97]
	v_mfma_f32_16x16x32_bf16 v[90:93], v[162:165], v[202:205], v[90:93]
	v_mfma_f32_16x16x32_bf16 v[78:81], v[154:157], v[212:215], v[78:81]
	v_mfma_f32_16x16x32_bf16 v[74:77], v[162:165], v[212:215], v[74:77]
	v_mfma_f32_16x16x32_bf16 v[126:129], v[158:161], v[190:193], v[126:129]
	v_mfma_f32_16x16x32_bf16 v[122:125], v[166:169], v[190:193], v[122:125]
	v_mfma_f32_16x16x32_bf16 v[110:113], v[158:161], v[198:201], v[110:113]
	v_mfma_f32_16x16x32_bf16 v[106:109], v[166:169], v[198:201], v[106:109]
	v_mfma_f32_16x16x32_bf16 v[94:97], v[158:161], v[206:209], v[94:97]
	v_mfma_f32_16x16x32_bf16 v[90:93], v[166:169], v[206:209], v[90:93]
	v_mfma_f32_16x16x32_bf16 v[78:81], v[158:161], v[216:219], v[78:81]
	v_mfma_f32_16x16x32_bf16 v[74:77], v[166:169], v[216:219], v[74:77]
	s_setprio 0
	s_setprio 1
	v_mfma_f32_16x16x32_bf16 v[118:121], v[170:173], v[186:189], v[118:121]
	v_mfma_f32_16x16x32_bf16 v[114:117], v[178:181], v[186:189], v[114:117]
	v_mfma_f32_16x16x32_bf16 v[102:105], v[170:173], v[194:197], v[102:105]
	v_mfma_f32_16x16x32_bf16 v[98:101], v[178:181], v[194:197], v[98:101]
	v_mfma_f32_16x16x32_bf16 v[86:89], v[170:173], v[202:205], v[86:89]
	v_mfma_f32_16x16x32_bf16 v[82:85], v[178:181], v[202:205], v[82:85]
	v_mfma_f32_16x16x32_bf16 v[70:73], v[170:173], v[212:215], v[70:73]
	v_mfma_f32_16x16x32_bf16 v[66:69], v[178:181], v[212:215], v[66:69]
	v_mfma_f32_16x16x32_bf16 v[118:121], v[174:177], v[190:193], v[118:121]
	v_mfma_f32_16x16x32_bf16 v[114:117], v[182:185], v[190:193], v[114:117]
	v_mfma_f32_16x16x32_bf16 v[102:105], v[174:177], v[198:201], v[102:105]
	v_mfma_f32_16x16x32_bf16 v[98:101], v[182:185], v[198:201], v[98:101]
	v_mfma_f32_16x16x32_bf16 v[86:89], v[174:177], v[206:209], v[86:89]
	v_mfma_f32_16x16x32_bf16 v[82:85], v[182:185], v[206:209], v[82:85]
	v_mfma_f32_16x16x32_bf16 v[70:73], v[174:177], v[216:219], v[70:73]
	v_mfma_f32_16x16x32_bf16 v[66:69], v[182:185], v[216:219], v[66:69]
	s_setprio 0
	s_barrier
; #define PG8_STAGE(bufoff, gbase, voff) do { _Pragma("unroll") for (int _i = 0; _i < 2; ++_i) \
;         __builtin_amdgcn_global_load_lds((const unsigned*)((const char*)(gbase) + (voff)[_i]), (PG8_LAS unsigned*)(lds + (bufoff) + ldsw + _i * 8192), 16, 0, 0); } while (0)
; #define PG8_LDA(dst, b, h) do { _Pragma("unroll") for (int m = 0; m < 4; ++m) _Pragma("unroll") for (int k = 0; k < 2; ++k) dst[m][k] = *(const PG8_LAS bf16x8*)(lds + PG8_SA(b, h) + aoff + m * 2048 + k * 1024); } while (0)
; #define PG8_MMA(ai, bj, At, Bt) do { __builtin_amdgcn_s_setprio(1); _Pragma("unroll") for (int m = 0; m < 4; ++m) _Pragma("unroll") for (int n = 0; n < 2; ++n) _Pragma("unroll") for (int k = 0; k < 2; ++k) \
;         acc[ai][bj][m][n] = __builtin_amdgcn_mfma_f32_16x16x32_bf16(Bt[n][k], At[m][k], acc[ai][bj][m][n], 0, 0, 0); __builtin_amdgcn_s_setprio(0); } while (0)
; #define PG8_WAIT_V(n) asm volatile("s_waitcnt vmcnt(" #n ")" ::: "memory")
; #define PG8_WAIT_L(n) asm volatile("s_waitcnt lgkmcnt(" #n ")" ::: "memory")
; #define PG8_BAR __builtin_amdgcn_s_barrier()
; #define PG8_SCHED __builtin_amdgcn_sched_barrier(0)
; template <class Epi, class Sched, bool ALIGN_EPI = false, bool SP2 = false>
; __device__ __forceinline__ void gemm_phase(PG8_LAS unsigned char* lds, const Gemm g, const Sched& S, const Epi& E) {
;     ...
;             PG8_LDA(At, 1, 1); PG8_STAGE(PG8_SB(1, 0), b3, voffB); PG8_STAGE(PG8_SB(1, 1), b3 + hstep, voffB); PG8_STAGE(PG8_SA(1, 0), a3, voffA);
;             PG8_WAIT_V(8); PG8_WAIT_L(0); PG8_BAR; PG8_MMA(1, 0, At, B0); PG8_MMA(1, 1, At, B1); PG8_BAR; PG8_SCHED;
	s_add_i32 s0, s69, s41
	v_lshl_add_u64 v[146:147], v[146:147], 0, s[8:9]
	s_mov_b32 m0, s0
	ds_read_b128 v[186:189], v152 offset:49152
	ds_read_b128 v[190:193], v152 offset:50176
	ds_read_b128 v[194:197], v152 offset:51200
	ds_read_b128 v[198:201], v152 offset:52224
	ds_read_b128 v[202:205], v152 offset:53248
	ds_read_b128 v[206:209], v152 offset:54272
	ds_read_b128 v[212:215], v152 offset:55296
	ds_read_b128 v[216:219], v152 offset:56320
	global_load_lds_dwordx4 v[146:147], off
	s_add_i32 m0, s0, 0x2000
	s_add_u32 s0, s34, 0x40080
	v_lshl_add_u64 v[146:147], v[220:221], 0, s[8:9]
	s_addc_u32 s1, s35, 0
	s_add_i32 s34, s70, s41
	global_load_lds_dwordx4 v[146:147], off
	v_lshl_add_u64 v[146:147], s[0:1], 0, v[132:133]
	s_mov_b32 m0, s34
	s_nop 0
	global_load_lds_dwordx4 v[146:147], off
	v_lshl_add_u64 v[146:147], s[0:1], 0, v[136:137]
	s_add_i32 m0, s34, 0x2000
	s_nop 0
	global_load_lds_dwordx4 v[146:147], off
	v_lshl_add_u64 v[146:147], v[222:223], 0, s[8:9]
	s_mov_b32 m0, s48
	s_nop 0
	global_load_lds_dwordx4 v[146:147], off
	v_lshl_add_u64 v[146:147], v[224:225], 0, s[8:9]
	s_mov_b32 m0, s49
	s_nop 0
	global_load_lds_dwordx4 v[146:147], off
	s_waitcnt vmcnt(8)
	s_waitcnt lgkmcnt(0)
	s_barrier
	s_setprio 1
	s_waitcnt lgkmcnt(0)
	v_mfma_f32_16x16x32_bf16 v[62:65], v[154:157], v[186:189], v[62:65]
	v_mfma_f32_16x16x32_bf16 v[58:61], v[162:165], v[186:189], v[58:61]
	v_mfma_f32_16x16x32_bf16 v[50:53], v[154:157], v[194:197], v[50:53]
	v_mfma_f32_16x16x32_bf16 v[42:45], v[162:165], v[194:197], v[42:45]
	v_mfma_f32_16x16x32_bf16 v[34:37], v[154:157], v[202:205], v[34:37]
	v_mfma_f32_16x16x32_bf16 v[26:29], v[162:165], v[202:205], v[26:29]
	v_mfma_f32_16x16x32_bf16 v[18:21], v[154:157], v[212:215], v[18:21]
	v_mfma_f32_16x16x32_bf16 v[10:13], v[162:165], v[212:215], v[10:13]
	v_mfma_f32_16x16x32_bf16 v[62:65], v[158:161], v[190:193], v[62:65]
	v_mfma_f32_16x16x32_bf16 v[58:61], v[166:169], v[190:193], v[58:61]
	v_mfma_f32_16x16x32_bf16 v[50:53], v[158:161], v[198:201], v[50:53]
	v_mfma_f32_16x16x32_bf16 v[42:45], v[166:169], v[198:201], v[42:45]
	v_mfma_f32_16x16x32_bf16 v[34:37], v[158:161], v[206:209], v[34:37]
	v_mfma_f32_16x16x32_bf16 v[26:29], v[166:169], v[206:209], v[26:29]
	v_mfma_f32_16x16x32_bf16 v[18:21], v[158:161], v[216:219], v[18:21]
	v_mfma_f32_16x16x32_bf16 v[10:13], v[166:169], v[216:219], v[10:13]
	s_setprio 0
	s_setprio 1
	v_mfma_f32_16x16x32_bf16 v[54:57], v[170:173], v[186:189], v[54:57]
	v_mfma_f32_16x16x32_bf16 v[46:49], v[178:181], v[186:189], v[46:49]
	v_mfma_f32_16x16x32_bf16 v[38:41], v[170:173], v[194:197], v[38:41]
	v_mfma_f32_16x16x32_bf16 v[30:33], v[178:181], v[194:197], v[30:33]
	v_mfma_f32_16x16x32_bf16 v[22:25], v[170:173], v[202:205], v[22:25]
	v_mfma_f32_16x16x32_bf16 v[14:17], v[178:181], v[202:205], v[14:17]
	v_mfma_f32_16x16x32_bf16 v[6:9], v[170:173], v[212:215], v[6:9]
	v_mfma_f32_16x16x32_bf16 v[2:5], v[178:181], v[212:215], v[2:5]
	v_mfma_f32_16x16x32_bf16 v[54:57], v[174:177], v[190:193], v[54:57]
	v_mfma_f32_16x16x32_bf16 v[46:49], v[182:185], v[190:193], v[46:49]
	v_mfma_f32_16x16x32_bf16 v[38:41], v[174:177], v[198:201], v[38:41]
	v_mfma_f32_16x16x32_bf16 v[30:33], v[182:185], v[198:201], v[30:33]
	v_mfma_f32_16x16x32_bf16 v[22:25], v[174:177], v[206:209], v[22:25]
	v_mfma_f32_16x16x32_bf16 v[14:17], v[182:185], v[206:209], v[14:17]
	v_mfma_f32_16x16x32_bf16 v[6:9], v[174:177], v[216:219], v[6:9]
	v_mfma_f32_16x16x32_bf16 v[2:5], v[182:185], v[216:219], v[2:5]
	s_setprio 0
	s_barrier
	s_add_i32 s68, s68, 2
	s_add_u32 s30, s30, 0x100
	s_addc_u32 s31, s31, 0
	s_add_u32 s60, s60, 0x100
	s_addc_u32 s61, s61, 0
	s_cmp_gt_u32 s68, 13
	s_cbranch_scc0 .LBB0_3723
	s_and_b64 vcc, exec, s[10:11]
	s_cbranch_vccz .LBB0_3726
	s_barrier
